# plus neighbourhood-attention local tiles: rel-pos bias reads batched (32 unconditional ds_read_b32, one wait, fmac+select) instead of 32 exec-masked branch+read+wait
# speedup vs baseline: 1.0852x; 1.0015x over previous
.LBB0_342:
	v_add_u32_e32 v50, v58, v141
	v_mov_b64_e32 v[60:61], s[26:27]
	s_movk_i32 s10, 0x1800
	v_mad_i64_i32 v[50:51], s[2:3], v50, s10, v[60:61]
	v_lshl_add_u64 v[50:51], v[50:51], 0, v[0:1]
	v_lshlrev_b32_e32 v62, 1, v124
	v_mov_b32_e32 v63, v1
	v_add_u32_e32 v58, v58, v143
	v_lshl_add_u64 v[50:51], v[50:51], 0, v[62:63]
	v_mad_i64_i32 v[58:59], s[2:3], v58, s10, v[60:61]
	v_add_co_u32_e32 v54, vcc, 0x1000, v50
	v_lshl_add_u64 v[58:59], v[58:59], 0, v[0:1]
	s_nop 0
	v_addc_co_u32_e32 v55, vcc, 0, v51, vcc
	v_lshl_add_u64 v[58:59], v[58:59], 0, v[62:63]
	v_add_co_u32_e32 v62, vcc, 0x1000, v58
	global_load_dwordx4 v[50:53], v[50:51], off offset:2048
	s_nop 0
	global_load_dwordx4 v[54:57], v[54:55], off
	v_addc_co_u32_e32 v63, vcc, 0, v59, vcc
	global_load_dwordx4 v[58:61], v[58:59], off offset:2048
	s_nop 0
	global_load_dwordx4 v[62:65], v[62:63], off
	s_and_b32 s15, s14, 64
	v_add_u32_e32 v66, s24, v148
	s_cmp_gt_u32 s24, 8
	s_cselect_b64 s[10:11], -1, 0
	s_cmp_lt_u32 s24, 9
	v_cmp_gt_u32_e32 vcc, 8, v66
	s_movk_i32 s13, 0x1800
	s_cselect_b64 s[28:29], -1, 0
	s_or_b64 s[2:3], s[10:11], vcc
	s_and_saveexec_b64 s[38:39], s[2:3]
	s_cbranch_execz .LBB0_337
	v_or_b32_e32 v66, s15, v138
	v_mad_u32_u24 v82, v66, s16, v145
	ds_read_b128 v[66:69], v82
	ds_read_b128 v[70:73], v82 offset:64
	ds_read_b128 v[74:77], v82 offset:2304
	ds_read_b128 v[78:81], v82 offset:2368
	ds_read_b128 v[90:93], v82 offset:4608
	ds_read_b128 v[94:97], v82 offset:4672
	ds_read_b128 v[110:113], v82 offset:6912
	ds_read_b128 v[150:153], v82 offset:6976
	s_waitcnt lgkmcnt(7)
	v_mfma_f32_16x16x32_bf16 v[82:85], v[66:69], v[38:41], 0
	v_mfma_f32_16x16x32_bf16 v[66:69], v[66:69], v[46:49], 0
	s_waitcnt lgkmcnt(6)
	v_mfma_f32_16x16x32_bf16 v[98:101], v[70:73], v[34:37], v[82:85]
	v_mfma_f32_16x16x32_bf16 v[82:85], v[70:73], v[42:45], v[66:69]
	s_waitcnt lgkmcnt(5)
	v_mfma_f32_16x16x32_bf16 v[66:69], v[74:77], v[38:41], 0
	v_mfma_f32_16x16x32_bf16 v[70:73], v[74:77], v[46:49], 0
	s_waitcnt lgkmcnt(4)
	v_mfma_f32_16x16x32_bf16 v[102:105], v[78:81], v[34:37], v[66:69]
	v_mfma_f32_16x16x32_bf16 v[86:89], v[78:81], v[42:45], v[70:73]
	s_waitcnt lgkmcnt(3)
	v_mfma_f32_16x16x32_bf16 v[66:69], v[90:93], v[38:41], 0
	v_mfma_f32_16x16x32_bf16 v[70:73], v[90:93], v[46:49], 0
	s_waitcnt lgkmcnt(2)
	v_mfma_f32_16x16x32_bf16 v[106:109], v[94:97], v[34:37], v[66:69]
	v_mfma_f32_16x16x32_bf16 v[90:93], v[94:97], v[42:45], v[70:73]
	s_waitcnt lgkmcnt(1)
	v_mfma_f32_16x16x32_bf16 v[66:69], v[110:113], v[38:41], 0
	v_mfma_f32_16x16x32_bf16 v[70:73], v[110:113], v[46:49], 0
	s_waitcnt lgkmcnt(0)
	v_mfma_f32_16x16x32_bf16 v[110:113], v[150:153], v[34:37], v[66:69]
	v_mfma_f32_16x16x32_bf16 v[94:97], v[150:153], v[42:45], v[70:73]
	s_mov_b64 s[30:31], -1
	s_and_b64 vcc, exec, s[28:29]
	s_cbranch_vccz .LBB0_377
	s_nop 0
	v_mov_b32_e32 v160, 0xf149f2ca
	ds_read_b32 v66, v147 offset:64
	ds_read_b32 v67, v147 offset:68
	ds_read_b32 v68, v147 offset:72
	ds_read_b32 v69, v147 offset:76
	ds_read_b32 v70, v147 offset:128
	ds_read_b32 v71, v147 offset:132
	ds_read_b32 v72, v147 offset:136
	ds_read_b32 v73, v147 offset:140
	ds_read_b32 v74, v147 offset:192
	ds_read_b32 v75, v147 offset:196
	ds_read_b32 v76, v147 offset:200
	ds_read_b32 v77, v147 offset:204
	ds_read_b32 v78, v147 offset:256
	ds_read_b32 v79, v147 offset:260
	ds_read_b32 v80, v147 offset:264
	ds_read_b32 v81, v147 offset:268
	s_waitcnt lgkmcnt(0)
	v_fmac_f32_e32 v66, 0x3e38aa3b, v98
	v_fmac_f32_e32 v67, 0x3e38aa3b, v99
	v_fmac_f32_e32 v68, 0x3e38aa3b, v100
	v_fmac_f32_e32 v69, 0x3e38aa3b, v101
	v_fmac_f32_e32 v70, 0x3e38aa3b, v102
	v_fmac_f32_e32 v71, 0x3e38aa3b, v103
	v_fmac_f32_e32 v72, 0x3e38aa3b, v104
	v_fmac_f32_e32 v73, 0x3e38aa3b, v105
	v_fmac_f32_e32 v74, 0x3e38aa3b, v106
	v_fmac_f32_e32 v75, 0x3e38aa3b, v107
	v_fmac_f32_e32 v76, 0x3e38aa3b, v108
	v_fmac_f32_e32 v77, 0x3e38aa3b, v109
	v_fmac_f32_e32 v78, 0x3e38aa3b, v110
	v_fmac_f32_e32 v79, 0x3e38aa3b, v111
	v_fmac_f32_e32 v80, 0x3e38aa3b, v112
	v_fmac_f32_e32 v81, 0x3e38aa3b, v113
	v_cndmask_b32_e64 v66, v160, v66, s[40:41]
	v_cndmask_b32_e64 v67, v160, v67, s[42:43]
	v_cndmask_b32_e64 v68, v160, v68, s[44:45]
	v_cndmask_b32_e64 v69, v160, v69, s[46:47]
	v_cndmask_b32_e64 v70, v160, v70, s[48:49]
	v_cndmask_b32_e64 v71, v160, v71, s[50:51]
	v_cndmask_b32_e64 v72, v160, v72, s[52:53]
	v_cndmask_b32_e64 v73, v160, v73, s[54:55]
	v_cndmask_b32_e64 v74, v160, v74, s[56:57]
	v_cndmask_b32_e64 v75, v160, v75, s[58:59]
	v_cndmask_b32_e64 v76, v160, v76, s[60:61]
	v_cndmask_b32_e64 v77, v160, v77, s[62:63]
	v_cndmask_b32_e64 v78, v160, v78, s[64:65]
	v_cndmask_b32_e64 v79, v160, v79, s[66:67]
	v_cndmask_b32_e64 v80, v160, v80, s[68:69]
	v_cndmask_b32_e64 v81, v160, v81, s[70:71]
	v_max3_f32 v150, v66, s18, v67
	v_max3_f32 v150, v150, v68, v69
	v_max3_f32 v150, v150, v70, v71
	v_max3_f32 v150, v150, v72, v73
	v_max3_f32 v150, v150, v74, v75
	v_max3_f32 v150, v150, v76, v77
	v_max3_f32 v150, v150, v78, v79
	v_max3_f32 v152, v150, v80, v81
	s_mov_b64 s[30:31], 0

.LBB0_381:
	s_andn2_b64 vcc, exec, s[28:29]
	s_mov_b64 s[2:3], -1
	s_cbranch_vccnz .LBB0_415
	v_mov_b32_e32 v160, 0xf149f2ca
	ds_read_b32 v98, v147
	ds_read_b32 v99, v147 offset:4
	ds_read_b32 v100, v147 offset:8
	ds_read_b32 v101, v147 offset:12
	ds_read_b32 v102, v147 offset:64
	ds_read_b32 v103, v147 offset:68
	ds_read_b32 v104, v147 offset:72
	ds_read_b32 v105, v147 offset:76
	ds_read_b32 v106, v147 offset:128
	ds_read_b32 v107, v147 offset:132
	ds_read_b32 v108, v147 offset:136
	ds_read_b32 v109, v147 offset:140
	ds_read_b32 v110, v147 offset:192
	ds_read_b32 v111, v147 offset:196
	ds_read_b32 v112, v147 offset:200
	ds_read_b32 v113, v147 offset:204
	s_waitcnt lgkmcnt(0)
	v_fmac_f32_e32 v98, 0x3e38aa3b, v82
	v_fmac_f32_e32 v99, 0x3e38aa3b, v83
	v_fmac_f32_e32 v100, 0x3e38aa3b, v84
	v_fmac_f32_e32 v101, 0x3e38aa3b, v85
	v_fmac_f32_e32 v102, 0x3e38aa3b, v86
	v_fmac_f32_e32 v103, 0x3e38aa3b, v87
	v_fmac_f32_e32 v104, 0x3e38aa3b, v88
	v_fmac_f32_e32 v105, 0x3e38aa3b, v89
	v_fmac_f32_e32 v106, 0x3e38aa3b, v90
	v_fmac_f32_e32 v107, 0x3e38aa3b, v91
	v_fmac_f32_e32 v108, 0x3e38aa3b, v92
	v_fmac_f32_e32 v109, 0x3e38aa3b, v93
	v_fmac_f32_e32 v110, 0x3e38aa3b, v94
	v_fmac_f32_e32 v111, 0x3e38aa3b, v95
	v_fmac_f32_e32 v112, 0x3e38aa3b, v96
	v_fmac_f32_e32 v113, 0x3e38aa3b, v97
	v_cndmask_b32_e64 v98, v160, v98, s[72:73]
	v_cndmask_b32_e64 v99, v160, v99, s[74:75]
	v_cndmask_b32_e64 v100, v160, v100, s[76:77]
	v_cndmask_b32_e64 v101, v160, v101, s[78:79]
	v_cndmask_b32_e64 v102, v160, v102, s[80:81]
	v_cndmask_b32_e64 v103, v160, v103, s[82:83]
	v_cndmask_b32_e64 v104, v160, v104, s[84:85]
	v_cndmask_b32_e64 v105, v160, v105, s[86:87]
	v_cndmask_b32_e64 v106, v160, v106, s[88:89]
	v_cndmask_b32_e64 v107, v160, v107, s[90:91]
	v_cndmask_b32_e64 v108, v160, v108, s[92:93]
	v_cndmask_b32_e64 v109, v160, v109, s[4:5]
	v_cndmask_b32_e64 v110, v160, v110, s[94:95]
	v_cndmask_b32_e64 v111, v160, v111, s[6:7]
	v_cndmask_b32_e64 v112, v160, v112, s[8:9]
	v_cndmask_b32_e64 v113, v160, v113, s[96:97]
	v_max3_f32 v152, v98, s18, v99
	v_max3_f32 v152, v152, v100, v101
	v_max3_f32 v152, v152, v102, v103
	v_max3_f32 v152, v152, v104, v105
	v_max3_f32 v152, v152, v106, v107
	v_max3_f32 v152, v152, v108, v109
	v_max3_f32 v152, v152, v110, v111
	v_max3_f32 v152, v152, v112, v113
	s_mov_b64 s[2:3], 0
